# nt also on phase-9 D1 delta loads (long evicted, streamed from HBM); x loads and out stores nt as before
# speedup vs baseline: 1.0232x; 1.0031x over previous
.LBB0_1455:
	v_lshl_add_u64 v[2:3], v[74:75], 0, v[68:69]
	global_load_dwordx4 v[26:29], v[2:3], off nt
	global_load_dwordx4 v[22:25], v[2:3], off offset:1024 nt
	global_load_dwordx4 v[10:13], v[2:3], off offset:2048 nt
	global_load_dwordx4 v[18:21], v[2:3], off offset:3072 nt
	global_load_dwordx2 v[44:45], v[66:67], off nt
	global_load_dwordx2 v[46:47], v[66:67], off offset:512 nt
	global_load_dwordx2 v[34:35], v[66:67], off offset:1024 nt
	global_load_dwordx2 v[36:37], v[66:67], off offset:1536 nt
	v_add_co_u32_e32 v2, vcc, 0xef000000, v66
	v_mov_b32_e32 v84, 0
	s_nop 0
	v_addc_co_u32_e32 v3, vcc, -1, v67, vcc
	v_add_co_u32_e32 v4, vcc, 0xef001000, v66
	v_mov_b32_e32 v85, 0
	s_nop 0
	v_addc_co_u32_e32 v5, vcc, -1, v67, vcc
	global_load_dwordx2 v[38:39], v[2:3], off
	global_load_dwordx2 v[42:43], v[4:5], off offset:-3584
	global_load_dwordx2 v[30:31], v[4:5], off offset:-3072
	global_load_dwordx2 v[32:33], v[4:5], off offset:-2560
	v_add_u32_e32 v2, s22, v52
	v_cmp_gt_i32_e64 s[0:1], s15, v2
	v_cmp_lt_i32_e32 vcc, s7, v2
	v_mov_b32_e32 v3, 0
	v_cndmask_b32_e64 v48, v52, v2, s[0:1]
	v_ashrrev_i32_e32 v49, 31, v48
	v_lshlrev_b64 v[4:5], 12, v[48:49]
	v_mov_b32_e32 v2, 0
	v_mov_b32_e32 v6, 0
	v_mov_b32_e32 v7, 0
	v_mov_b32_e32 v8, 0
	v_mov_b32_e32 v9, 0
	v_mov_b32_e32 v40, 0
	v_mov_b32_e32 v41, 0
	v_mov_b32_e32 v76, 0
	v_mov_b32_e32 v77, 0
	v_mov_b32_e32 v14, 0
	v_mov_b32_e32 v15, 0
	v_mov_b32_e32 v16, 0
	v_mov_b32_e32 v17, 0
	s_and_saveexec_b64 s[2:3], s[0:1]
	s_cbranch_execz .LBB0_1457
	v_lshlrev_b64 v[2:3], 11, v[48:49]
	v_lshl_add_u64 v[6:7], v[62:63], 0, v[2:3]
	v_lshl_add_u64 v[2:3], v[64:65], 0, v[2:3]
	global_load_dwordx2 v[40:41], v[6:7], off nt
	global_load_dwordx2 v[80:81], v[2:3], off
	global_load_dwordx2 v[82:83], v[6:7], off offset:512 nt
	global_load_dwordx2 v[84:85], v[2:3], off offset:512
	global_load_dwordx2 v[86:87], v[6:7], off offset:1024 nt
	global_load_dwordx2 v[88:89], v[2:3], off offset:1024
	global_load_dwordx2 v[90:91], v[6:7], off offset:1536 nt
	global_load_dwordx2 v[92:93], v[2:3], off offset:1536
	v_lshl_add_u64 v[2:3], v[60:61], 0, v[4:5]
	global_load_dwordx4 v[6:9], v[2:3], off nt
	global_load_dwordx4 v[14:17], v[2:3], off offset:1024 nt
	global_load_dwordx4 v[48:51], v[2:3], off offset:2048 nt
	global_load_dwordx4 v[76:79], v[2:3], off offset:3072 nt
	s_waitcnt vmcnt(10)
	v_lshlrev_b32_e32 v94, 16, v80
	s_waitcnt vmcnt(9)
	v_lshlrev_b32_e32 v96, 16, v82
	v_and_b32_e32 v97, 0xffff0000, v82
	s_waitcnt vmcnt(8)
	v_lshlrev_b32_e32 v98, 16, v84
	v_and_b32_e32 v99, 0xffff0000, v84
	v_lshlrev_b32_e32 v2, 16, v40
	v_and_b32_e32 v3, 0xffff0000, v40
	v_lshlrev_b32_e32 v40, 16, v41
	v_and_b32_e32 v41, 0xffff0000, v41
	v_lshlrev_b32_e32 v82, 16, v83
	v_and_b32_e32 v83, 0xffff0000, v83
	v_lshlrev_b32_e32 v100, 16, v85
	v_and_b32_e32 v101, 0xffff0000, v85
	s_waitcnt vmcnt(7)
	v_lshlrev_b32_e32 v84, 16, v86
	v_and_b32_e32 v85, 0xffff0000, v86
	v_lshlrev_b32_e32 v86, 16, v87
	v_and_b32_e32 v87, 0xffff0000, v87
	s_waitcnt vmcnt(5)
	v_lshlrev_b32_e32 v108, 16, v90
	v_and_b32_e32 v109, 0xffff0000, v90
	v_lshlrev_b32_e32 v90, 16, v91
	v_and_b32_e32 v91, 0xffff0000, v91
	v_and_b32_e32 v95, 0xffff0000, v80
	v_lshlrev_b32_e32 v80, 16, v81
	v_and_b32_e32 v81, 0xffff0000, v81
	v_lshlrev_b32_e32 v106, 16, v88
	v_and_b32_e32 v107, 0xffff0000, v88
	v_lshlrev_b32_e32 v88, 16, v89
	v_and_b32_e32 v89, 0xffff0000, v89
	s_waitcnt vmcnt(4)
	v_lshlrev_b32_e32 v110, 16, v92
	v_and_b32_e32 v111, 0xffff0000, v92
	v_lshlrev_b32_e32 v92, 16, v93
	v_and_b32_e32 v93, 0xffff0000, v93
	s_waitcnt vmcnt(3)
	v_pk_add_f32 v[2:3], v[6:7], v[2:3]
	v_pk_add_f32 v[6:7], v[8:9], v[40:41]
	s_waitcnt vmcnt(2)
	v_pk_add_f32 v[8:9], v[14:15], v[96:97]
	v_pk_add_f32 v[14:15], v[16:17], v[82:83]
	s_waitcnt vmcnt(1)
	v_pk_add_f32 v[16:17], v[48:49], v[84:85]
	v_pk_add_f32 v[48:49], v[50:51], v[86:87]
	s_waitcnt vmcnt(0)
	v_pk_add_f32 v[50:51], v[76:77], v[108:109]
	v_pk_add_f32 v[78:79], v[78:79], v[90:91]
	v_pk_add_f32 v[2:3], v[2:3], v[94:95]
	v_pk_add_f32 v[84:85], v[6:7], v[80:81]
	v_pk_add_f32 v[6:7], v[8:9], v[98:99]
	v_pk_add_f32 v[8:9], v[14:15], v[100:101]
	v_pk_add_f32 v[40:41], v[16:17], v[106:107]
	v_pk_add_f32 v[76:77], v[48:49], v[88:89]
	v_pk_add_f32 v[14:15], v[50:51], v[110:111]
	v_pk_add_f32 v[16:17], v[78:79], v[92:93]
